# NA local loop: waves 4-7 issue their K/V DMA after the tile compute (stagger vs waves 0-3)
# baseline (speedup 1.0000x reference)
; #define LAS __attribute__((address_space(3)))
; __device__ __forceinline__ void na_local_tile(f32x4 (&O)[4][4], float (&ls)[4], const bf16x8 (&qf)[4][2], float negb,
;                                               const LAS unsigned char* Kt, const LAS unsigned char* Vt, int lane, const LAS float* bias_row, bool rowvalid) {
;     const int l15 = lane & 15, g = lane >> 4, q4 = l15 >> 2;
;     const LAS unsigned char* kb0 = Kt + l15 * 128;
;     const int kx0 = ((g) ^ (l15 & 7)) << 4, kx1 = ((4 + g) ^ (l15 & 7)) << 4;
;     const LAS unsigned char* vrow = Vt + (4 * g + q4) * 128 + (lane & 3) * 8;
;     const int swz = (2 * (g & 1) + (q4 >> 1)) & 3;
; #pragma unroll
;     for (int grp = 0; grp < 4; ++grp) {
;         const int kwin = grp == 0 ? 0 : (grp == 1 ? 8 : (grp == 2 ? 24 : 32));
;         f32x4 S[2];
; #pragma unroll
;         for (int k2 = 0; k2 < 2; ++k2) {
;             const bf16x8 kf0 = *(const LAS bf16x8*)(kb0 + (kwin + 16 * k2) * 128 + kx0), kf1 = *(const LAS bf16x8*)(kb0 + (kwin + 16 * k2) * 128 + kx1);
;             S[k2] = __builtin_amdgcn_mfma_f32_16x16x32_bf16(kf0, qf[grp][0], (f32x4){negb, negb, negb, negb}, 0, 0, 0);
;             S[k2] = __builtin_amdgcn_mfma_f32_16x16x32_bf16(kf1, qf[grp][1], S[k2], 0, 0, 0); }
;         const int c = 16 * grp + l15; const int c0 = rowvalid ? min(max(c - 8, 0), 48) : 4096;
;         const LAS float* bl = bias_row + (15 - c + 4 * g);
; #pragma unroll
;         for (int k2 = 0; k2 < 2; ++k2)
; #pragma unroll
;             for (int i = 0; i < 4; ++i) { const int kc = kwin + 16 * k2 + 4 * g + i; const float bias = bl[kwin + 16 * k2 + i];
;                 S[k2][i] = ((unsigned)(kc - c0) < 16u) ? S[k2][i] + bias : NEGBIG; }
;         ls[grp] += exp_step<2>(S);
;         const bf16x8 pf = pack8(S[0], S[1]);
; __device__ __forceinline__ void na_phase(LAS unsigned char* lds, const bf16_t* Q, const bf16_t* K, const bf16_t* V, bf16_t* Ob, const float* rpb, float negb) {
;     ...
;         for (int t = 4; t < NT; ++t) {
;             dma_tile<2>(lds + ((t + 3) & 3) * NA_BUF, K, V, NA_ROW0(t + 3), DM, dl, w);
;             const LAS unsigned char* buf = lds + (t & 3) * NA_BUF;
;             const int kr = kr_lo + t - 4; const bool rv = kr >= r0w && kr < r0w + 8;
;             if (rv) na_local_tile(O, ls, qf, negb, buf + hh * 8192, buf + 2 * 8192 + hh * 8192, lane, tab + hh * 512 + (kr - r + 7) * 31, true);
.LBB0_383:
	v_readlane_b32 s99, v240, 49
	s_nop 0
	s_cmp_lg_u32 s99, 0
	s_cbranch_scc1 .Lna_skip_top_dma
	s_add_i32 s60, s6, 0x18000
	s_and_b32 s60, s60, 0x18000
	s_add_i32 s7, s97, 7
	s_add_i32 vcc_lo, s60, 0
	s_cmp_lt_i32 s7, s93
	s_cselect_b32 s61, s66, 0
	s_cselect_b32 s60, s59, s82
	s_lshl_b64 s[60:61], s[60:61], 11
	s_add_u32 s76, s67, s60
	s_addc_u32 s77, s4, s61
	s_add_u32 s60, s5, s60
	s_addc_u32 s61, s58, s61
	s_add_i32 s7, s63, vcc_lo
	s_add_i32 vcc_lo, s7, 0x4000
	s_mov_b32 vcc_hi, m0
	s_mov_b32 m0, s7
	s_nop 0
	global_load_lds_dwordx4 v221, s[76:77]
	s_mov_b32 m0, vcc_hi
	s_nop 0
	s_mov_b32 vcc_hi, m0
	s_mov_b32 m0, vcc_lo
	s_nop 0
	global_load_lds_dwordx4 v222, s[60:61]
	s_mov_b32 m0, vcc_hi
	s_add_i32 vcc_lo, s7, 0x2000
	s_mov_b32 vcc_hi, m0
	s_mov_b32 m0, vcc_lo
	s_nop 0
	global_load_lds_dwordx4 v223, s[76:77]
	s_mov_b32 m0, vcc_hi
	s_addk_i32 s7, 0x6000
	s_mov_b32 s76, m0
	s_mov_b32 m0, s7
	s_nop 0
	global_load_lds_dwordx4 v224, s[60:61]
	s_mov_b32 m0, s76
.Lna_skip_top_dma:
	s_add_i32 s7, s68, s97
	s_cmp_ge_u32 s7, s94
	s_cselect_b64 s[60:61], -1, 0
	s_cmp_lt_u32 s7, s95
	s_cselect_b64 s[76:77], -1, 0
	s_and_b64 s[60:61], s[60:61], s[76:77]
	s_andn2_b64 vcc, exec, s[60:61]
	s_cbranch_vccnz .Lna_after_body
	s_and_b32 s7, s6, 0x18000
	s_add_i32 s7, s65, s7
	s_mov_b32 s76, 0x20000
	v_add3_u32 v236, v129, v110, s76
	v_add_u32_e32 v130, s7, v111
	v_mov_b32_e32 v238, 0xf149f2ca
	v_add3_u32 v235, s7, v210, v205
	ds_read2_b32 v[228:229], v236 offset0:108 offset1:109
	ds_read2_b32 v[230:231], v236 offset0:110 offset1:111
	ds_read2_b32 v[104:105], v236 offset0:124 offset1:125
	ds_read2_b32 v[106:107], v236 offset0:126 offset1:127
	v_add_u32_e32 v131, v130, v204
	v_add_u32_e32 v130, v130, v203
	ds_read2_b32 v[140:141], v236 offset0:100 offset1:101
	ds_read2_b32 v[142:143], v236 offset0:102 offset1:103
	ds_read2_b32 v[144:145], v236 offset0:116 offset1:117
	ds_read2_b32 v[146:147], v236 offset0:118 offset1:119
	ds_read2_b32 v[148:149], v236 offset0:92 offset1:93
	ds_read2_b32 v[150:151], v236 offset0:94 offset1:95
	ds_read_b128 v[160:163], v130
	ds_read_b128 v[164:167], v131
	ds_read_b128 v[168:171], v130 offset:2048
	ds_read_b128 v[172:175], v131 offset:2048
	v_add_u32_e32 v232, v235, v206
	v_add_u32_e32 v233, v235, v207
	v_add_u32_e32 v234, v235, v208
	v_add_u32_e32 v235, v235, v209
	s_waitcnt lgkmcnt(4)
	v_cndmask_b32_e64 v100, v238, v228, s[8:9]
	v_cndmask_b32_e64 v101, v238, v229, s[10:11]
	v_cndmask_b32_e64 v102, v238, v230, s[12:13]
	v_cndmask_b32_e64 v103, v238, v231, s[14:15]
	v_cndmask_b32_e64 v104, v238, v104, s[16:17]
	v_cndmask_b32_e64 v105, v238, v105, s[18:19]
	v_cndmask_b32_e64 v106, v238, v106, s[20:21]
	v_cndmask_b32_e64 v107, v238, v107, s[22:23]
	ds_read_b128 v[176:179], v130 offset:1024
	ds_read_b128 v[180:183], v131 offset:1024
	ds_read_b128 v[184:187], v130 offset:3072
	ds_read_b128 v[188:191], v131 offset:3072
	s_waitcnt lgkmcnt(4)
	v_mfma_f32_16x16x32_bf16 v[100:103], v[160:163], v[4:7], v[100:103]
	v_mfma_f32_16x16x32_bf16 v[104:107], v[168:171], v[4:7], v[104:107]
	v_mfma_f32_16x16x32_bf16 v[100:103], v[164:167], v[8:11], v[100:103]
	v_mfma_f32_16x16x32_bf16 v[104:107], v[172:175], v[8:11], v[104:107]
	ds_read_b64_tr_b16 v[160:161], v232 offset:16384
	ds_read_b64_tr_b16 v[162:163], v232 offset:18432
	ds_read_b64_tr_b16 v[164:165], v233 offset:16384
	ds_read_b64_tr_b16 v[166:167], v233 offset:18432
	ds_read_b64_tr_b16 v[168:169], v234 offset:16384
	ds_read_b64_tr_b16 v[170:171], v234 offset:18432
	ds_read_b64_tr_b16 v[172:173], v235 offset:16384
	ds_read_b64_tr_b16 v[174:175], v235 offset:18432
	v_cndmask_b32_e64 v140, v238, v140, s[24:25]
	v_cndmask_b32_e64 v141, v238, v141, s[26:27]
	v_cndmask_b32_e64 v142, v238, v142, s[28:29]
	v_cndmask_b32_e64 v143, v238, v143, s[30:31]
	v_cndmask_b32_e64 v144, v238, v144, s[34:35]
	v_cndmask_b32_e64 v145, v238, v145, s[36:37]
	v_cndmask_b32_e64 v146, v238, v146, s[38:39]
	v_cndmask_b32_e64 v147, v238, v147, s[40:41]
	v_cndmask_b32_e64 v148, v238, v148, s[42:43]
	v_cndmask_b32_e64 v149, v238, v149, s[44:45]
	v_cndmask_b32_e64 v150, v238, v150, s[46:47]
	v_cndmask_b32_e64 v151, v238, v151, s[48:49]
	v_cndmask_b32_e64 v228, v238, v228, s[50:51]
	v_cndmask_b32_e64 v229, v238, v229, s[52:53]
	v_cndmask_b32_e64 v230, v238, v230, s[54:55]
	v_cndmask_b32_e64 v231, v238, v231, s[56:57]
	s_waitcnt lgkmcnt(8)
	v_mfma_f32_16x16x32_bf16 v[132:135], v[176:179], v[12:15], v[140:143]
	v_mfma_f32_16x16x32_bf16 v[136:139], v[184:187], v[12:15], v[144:147]
	v_mfma_f32_16x16x32_bf16 v[132:135], v[180:183], v[16:19], v[132:135]
	v_mfma_f32_16x16x32_bf16 v[136:139], v[188:191], v[16:19], v[136:139]
	v_exp_f32_e32 v100, v100
	v_exp_f32_e32 v101, v101
	v_exp_f32_e32 v102, v102
	v_add_f32_e32 v154, v100, v101
	v_exp_f32_e32 v103, v103
	v_exp_f32_e32 v104, v104
	v_add_f32_e32 v154, v154, v102
	v_exp_f32_e32 v105, v105
	v_add_f32_e32 v154, v154, v103
	v_exp_f32_e32 v106, v106
	v_add_f32_e32 v154, v154, v104
	v_exp_f32_e32 v107, v107
	v_add_f32_e32 v154, v154, v105
	v_cvt_pk_bf16_f32 v100, v100, v101
	v_add_f32_e32 v154, v154, v106
	v_cvt_pk_bf16_f32 v101, v102, v103
	v_cvt_pk_bf16_f32 v102, v104, v105
	v_cvt_pk_bf16_f32 v103, v106, v107
	v_add_f32_e32 v154, v154, v107
	v_add_f32_e32 v126, v126, v154
	s_waitcnt lgkmcnt(0)
; #define LAS __attribute__((address_space(3)))
; __device__ __forceinline__ s16x4 vtr(const LAS unsigned char* p) { return __builtin_bit_cast(s16x4, __builtin_amdgcn_ds_read_tr16_b64_v4i16((LAS v4i16_t*)p)); }
; __device__ __forceinline__ bf16x8 cat8(s16x4 a, s16x4 b) { return (bf16x8){a[0], a[1], a[2], a[3], b[0], b[1], b[2], b[3]}; }
; __device__ __forceinline__ bf16x8 pack8(const f32x4& a, const f32x4& b) { u32x4 w; w.x = pkbf(a[0], a[1]); w.y = pkbf(a[2], a[3]); w.z = pkbf(b[0], b[1]); w.w = pkbf(b[2], b[3]); return __builtin_bit_cast(bf16x8, w); }
; template <int NHT> __device__ __forceinline__ void dma_tile(LAS unsigned char* buf, const bf16_t* Kg, const bf16_t* Vg, size_t row0, int pitch, const DmaLane& d, int w) {
;     const unsigned char* kb = (const unsigned char*)Kg + row0 * (size_t)pitch * 2; const unsigned char* vb = (const unsigned char*)Vg + row0 * (size_t)pitch * 2;
;     const unsigned l0 = (unsigned)__builtin_amdgcn_readfirstlane((int)(unsigned)(uintptr_t)buf + w * 1024);
; #pragma unroll
;     for (int hh = 0; hh < NHT; ++hh) {
;         glds16(kb, d.koff + hh * 128, l0 + hh * 8192);
;         glds16(vb, d.voff + hh * 128, l0 + NHT * 8192 + hh * 8192); }
; __device__ __forceinline__ void na_local_tile(f32x4 (&O)[4][4], float (&ls)[4], const bf16x8 (&qf)[4][2], float negb,
;                                               const LAS unsigned char* Kt, const LAS unsigned char* Vt, int lane, const LAS float* bias_row, bool rowvalid) {
;     ...
;             for (int i = 0; i < 4; ++i) { const int kc = kwin + 16 * k2 + 4 * g + i; const float bias = bl[kwin + 16 * k2 + i];
;                 S[k2][i] = ((unsigned)(kc - c0) < 16u) ? S[k2][i] + bias : NEGBIG; }
;         ls[grp] += exp_step<2>(S);
;         const bf16x8 pf = pack8(S[0], S[1]);
; #pragma unroll
;         for (int db = 0; db < 4; ++db) {
;             const LAS unsigned char* va = vrow + ((db ^ swz) << 5) + kwin * 128;
;             const bf16x8 vf = cat8(vtr(va), vtr(va + 16 * 128));
;             O[grp][db] = __builtin_amdgcn_mfma_f32_16x16x32_bf16(vf, pf, O[grp][db], 0, 0, 0);
;         }
;         __builtin_amdgcn_sched_barrier(0x108);
	v_mfma_f32_16x16x32_bf16 v[48:51], v[160:163], v[100:103], v[48:51]
	v_mfma_f32_16x16x32_bf16 v[44:47], v[164:167], v[100:103], v[44:47]
	v_mfma_f32_16x16x32_bf16 v[40:43], v[168:171], v[100:103], v[40:43]
	v_mfma_f32_16x16x32_bf16 v[36:39], v[172:175], v[100:103], v[36:39]
	ds_read_b128 v[160:163], v130 offset:3072
	ds_read_b128 v[164:167], v131 offset:3072
	ds_read_b128 v[168:171], v130 offset:5120
	ds_read_b128 v[172:175], v131 offset:5120
	ds_read_b64_tr_b16 v[176:177], v232 offset:17408
	ds_read_b64_tr_b16 v[178:179], v232 offset:19456
	ds_read_b64_tr_b16 v[180:181], v233 offset:17408
	ds_read_b64_tr_b16 v[182:183], v233 offset:19456
	ds_read_b64_tr_b16 v[184:185], v234 offset:17408
	ds_read_b64_tr_b16 v[186:187], v234 offset:19456
	ds_read_b64_tr_b16 v[188:189], v235 offset:17408
	ds_read_b64_tr_b16 v[190:191], v235 offset:19456
	v_exp_f32_e32 v132, v132
	v_exp_f32_e32 v133, v133
	v_exp_f32_e32 v134, v134
	v_add_f32_e32 v154, v132, v133
	v_exp_f32_e32 v135, v135
	v_exp_f32_e32 v136, v136
	v_add_f32_e32 v154, v154, v134
	v_exp_f32_e32 v137, v137
	v_add_f32_e32 v154, v154, v135
	v_exp_f32_e32 v138, v138
	v_add_f32_e32 v154, v154, v136
	v_exp_f32_e32 v139, v139
	v_add_f32_e32 v154, v154, v137
	v_cvt_pk_bf16_f32 v132, v132, v133
	v_add_f32_e32 v154, v154, v138
	v_cvt_pk_bf16_f32 v133, v134, v135
	v_cvt_pk_bf16_f32 v134, v136, v137
	v_cvt_pk_bf16_f32 v135, v138, v139
	v_add_f32_e32 v154, v154, v139
	v_add_f32_e32 v127, v127, v154
	s_waitcnt lgkmcnt(0)
	v_mfma_f32_16x16x32_bf16 v[64:67], v[176:179], v[132:135], v[64:67]
	v_mfma_f32_16x16x32_bf16 v[60:63], v[180:183], v[132:135], v[60:63]
	v_mfma_f32_16x16x32_bf16 v[56:59], v[184:187], v[132:135], v[56:59]
	v_mfma_f32_16x16x32_bf16 v[52:55], v[188:191], v[132:135], v[52:55]
	v_mfma_f32_16x16x32_bf16 v[140:143], v[160:163], v[20:23], v[140:143]
	v_mfma_f32_16x16x32_bf16 v[144:147], v[168:171], v[20:23], v[144:147]
	v_mfma_f32_16x16x32_bf16 v[140:143], v[164:167], v[24:27], v[140:143]
	v_mfma_f32_16x16x32_bf16 v[144:147], v[172:175], v[24:27], v[144:147]
	ds_read_b128 v[176:179], v130 offset:4096
	ds_read_b128 v[180:183], v131 offset:4096
	ds_read_b128 v[184:187], v130 offset:6144
	ds_read_b128 v[188:191], v131 offset:6144
	ds_read_b64_tr_b16 v[160:161], v232 offset:19456
	ds_read_b64_tr_b16 v[162:163], v232 offset:21504
	ds_read_b64_tr_b16 v[164:165], v233 offset:19456
	ds_read_b64_tr_b16 v[166:167], v233 offset:21504
	ds_read_b64_tr_b16 v[168:169], v234 offset:19456
	ds_read_b64_tr_b16 v[170:171], v234 offset:21504
	ds_read_b64_tr_b16 v[172:173], v235 offset:19456
	ds_read_b64_tr_b16 v[174:175], v235 offset:21504
	v_exp_f32_e32 v140, v140
	v_exp_f32_e32 v141, v141
	v_exp_f32_e32 v142, v142
	v_add_f32_e32 v154, v140, v141
	v_exp_f32_e32 v143, v143
	v_exp_f32_e32 v144, v144
	v_add_f32_e32 v154, v154, v142
	v_exp_f32_e32 v145, v145
	v_add_f32_e32 v154, v154, v143
	v_exp_f32_e32 v146, v146
	v_add_f32_e32 v154, v154, v144
	v_exp_f32_e32 v147, v147
	v_add_f32_e32 v154, v154, v145
	v_cvt_pk_bf16_f32 v140, v140, v141
	v_add_f32_e32 v154, v154, v146
	v_cvt_pk_bf16_f32 v141, v142, v143
	v_cvt_pk_bf16_f32 v142, v144, v145
	v_cvt_pk_bf16_f32 v143, v146, v147
	v_add_f32_e32 v154, v154, v147
	v_add_f32_e32 v124, v124, v154
	s_waitcnt lgkmcnt(8)
	v_mfma_f32_16x16x32_bf16 v[148:151], v[176:179], v[28:31], v[148:151]
	v_mfma_f32_16x16x32_bf16 v[228:231], v[184:187], v[28:31], v[228:231]
	v_mfma_f32_16x16x32_bf16 v[148:151], v[180:183], v[32:35], v[148:151]
	v_mfma_f32_16x16x32_bf16 v[228:231], v[188:191], v[32:35], v[228:231]
	s_waitcnt lgkmcnt(0)
	v_mfma_f32_16x16x32_bf16 v[80:83], v[160:163], v[140:143], v[80:83]
	v_mfma_f32_16x16x32_bf16 v[76:79], v[164:167], v[140:143], v[76:79]
	v_mfma_f32_16x16x32_bf16 v[72:75], v[168:171], v[140:143], v[72:75]
	v_mfma_f32_16x16x32_bf16 v[68:71], v[172:175], v[140:143], v[68:71]
	ds_read_b64_tr_b16 v[176:177], v232 offset:20480
	ds_read_b64_tr_b16 v[178:179], v232 offset:22528
	ds_read_b64_tr_b16 v[180:181], v233 offset:20480
	ds_read_b64_tr_b16 v[182:183], v233 offset:22528
	ds_read_b64_tr_b16 v[184:185], v234 offset:20480
	ds_read_b64_tr_b16 v[186:187], v234 offset:22528
	ds_read_b64_tr_b16 v[188:189], v235 offset:20480
	ds_read_b64_tr_b16 v[190:191], v235 offset:22528
	v_exp_f32_e32 v148, v148
	v_exp_f32_e32 v149, v149
	v_exp_f32_e32 v150, v150
	v_add_f32_e32 v154, v148, v149
	v_exp_f32_e32 v151, v151
	v_exp_f32_e32 v228, v228
	v_add_f32_e32 v154, v154, v150
	v_exp_f32_e32 v229, v229
	v_add_f32_e32 v154, v154, v151
	v_exp_f32_e32 v230, v230
	v_add_f32_e32 v154, v154, v228
	v_exp_f32_e32 v231, v231
	v_add_f32_e32 v154, v154, v229
	v_cvt_pk_bf16_f32 v148, v148, v149
	v_add_f32_e32 v154, v154, v230
	v_cvt_pk_bf16_f32 v149, v150, v151
	v_cvt_pk_bf16_f32 v150, v228, v229
	v_cvt_pk_bf16_f32 v151, v230, v231
	v_add_f32_e32 v154, v154, v231
	v_add_f32_e32 v125, v125, v154
	s_waitcnt lgkmcnt(0)
	v_mfma_f32_16x16x32_bf16 v[84:87], v[176:179], v[148:151], v[84:87]
	v_mfma_f32_16x16x32_bf16 v[92:95], v[180:183], v[148:151], v[92:95]
	v_mfma_f32_16x16x32_bf16 v[88:91], v[184:187], v[148:151], v[88:91]
	v_mfma_f32_16x16x32_bf16 v[96:99], v[188:191], v[148:151], v[96:99]
.Lna_after_body:
	s_cmp_eq_u32 s99, 0
	s_cbranch_scc1 .LBB0_382
	s_add_i32 s60, s6, 0x18000
	s_and_b32 s60, s60, 0x18000
	s_add_i32 s7, s97, 7
	s_add_i32 vcc_lo, s60, 0
	s_cmp_lt_i32 s7, s93
	s_cselect_b32 s61, s66, 0
	s_cselect_b32 s60, s59, s82
	s_lshl_b64 s[60:61], s[60:61], 11
	s_add_u32 s76, s67, s60
	s_addc_u32 s77, s4, s61
	s_add_u32 s60, s5, s60
	s_addc_u32 s61, s58, s61
	s_add_i32 s7, s63, vcc_lo
	s_add_i32 vcc_lo, s7, 0x4000
	s_mov_b32 vcc_hi, m0
	s_mov_b32 m0, s7
	s_nop 0
	global_load_lds_dwordx4 v221, s[76:77]
	s_mov_b32 m0, vcc_hi
	s_nop 0
	s_mov_b32 vcc_hi, m0
	s_mov_b32 m0, vcc_lo
	s_nop 0
	global_load_lds_dwordx4 v222, s[60:61]
	s_mov_b32 m0, vcc_hi
	s_add_i32 vcc_lo, s7, 0x2000
	s_mov_b32 vcc_hi, m0
	s_mov_b32 m0, vcc_lo
	s_nop 0
	global_load_lds_dwordx4 v223, s[76:77]
	s_mov_b32 m0, vcc_hi
	s_addk_i32 s7, 0x6000
	s_mov_b32 s76, m0
	s_mov_b32 m0, s7
	s_nop 0
	global_load_lds_dwordx4 v224, s[60:61]
	s_mov_b32 m0, s76
	s_branch .LBB0_382

; __global__ void __launch_bounds__(512, 2) fwd_megakernel(Args a) {
	.amdhsa_kernel _Z14fwd_megakernel4Args
		.amdhsa_group_segment_fixed_size 0
		.amdhsa_private_segment_fixed_size 0
		.amdhsa_kernarg_size 432
		.amdhsa_user_sgpr_count 2
		.amdhsa_user_sgpr_dispatch_ptr 0
		.amdhsa_user_sgpr_queue_ptr 0
		.amdhsa_user_sgpr_kernarg_segment_ptr 1
		.amdhsa_user_sgpr_dispatch_id 0
		.amdhsa_user_sgpr_kernarg_preload_length 0
		.amdhsa_user_sgpr_kernarg_preload_offset 0
		.amdhsa_user_sgpr_private_segment_size 0
		.amdhsa_uses_dynamic_stack 0
		.amdhsa_enable_private_segment 0
		.amdhsa_system_sgpr_workgroup_id_x 1
		.amdhsa_system_sgpr_workgroup_id_y 0
		.amdhsa_system_sgpr_workgroup_id_z 0
		.amdhsa_system_sgpr_workgroup_info 0
		.amdhsa_system_vgpr_workitem_id 2
		.amdhsa_next_free_vgpr 242
		.amdhsa_next_free_sgpr 100
		.amdhsa_accum_offset 244
		.amdhsa_reserve_vcc 1
		.amdhsa_float_round_mode_32 0
		.amdhsa_float_round_mode_16_64 0
		.amdhsa_float_denorm_mode_32 3
		.amdhsa_float_denorm_mode_16_64 3
		.amdhsa_dx10_clamp 1
		.amdhsa_ieee_mode 1
		.amdhsa_fp16_overflow 0
		.amdhsa_tg_split 0
		.amdhsa_exception_fp_ieee_invalid_op 0
		.amdhsa_exception_fp_denorm_src 0
		.amdhsa_exception_fp_ieee_div_zero 0
		.amdhsa_exception_fp_ieee_overflow 0
		.amdhsa_exception_fp_ieee_underflow 0
		.amdhsa_exception_fp_ieee_inexact 0
		.amdhsa_exception_int_div_zero 0
	.end_amdhsa_kernel

; __global__ void __launch_bounds__(512, 2) fwd_megakernel(Args a) {
amdhsa.kernels:
  - .agpr_count:     0
    .args:
      - .offset:         0
        .size:           176
        .value_kind:     by_value
      - .offset:         176
        .size:           4
        .value_kind:     hidden_block_count_x
      - .offset:         180
        .size:           4
        .value_kind:     hidden_block_count_y
      - .offset:         184
        .size:           4
        .value_kind:     hidden_block_count_z
      - .offset:         188
        .size:           2
        .value_kind:     hidden_group_size_x
      - .offset:         190
        .size:           2
        .value_kind:     hidden_group_size_y
      - .offset:         192
        .size:           2
        .value_kind:     hidden_group_size_z
      - .offset:         194
        .size:           2
        .value_kind:     hidden_remainder_x
      - .offset:         196
        .size:           2
        .value_kind:     hidden_remainder_y
      - .offset:         198
        .size:           2
        .value_kind:     hidden_remainder_z
      - .offset:         216
        .size:           8
        .value_kind:     hidden_global_offset_x
      - .offset:         224
        .size:           8
        .value_kind:     hidden_global_offset_y
      - .offset:         232
        .size:           8
        .value_kind:     hidden_global_offset_z
      - .offset:         240
        .size:           2
        .value_kind:     hidden_grid_dims
      - .offset:         264
        .size:           8
        .value_kind:     hidden_multigrid_sync_arg
      - .offset:         296
        .size:           4
        .value_kind:     hidden_dynamic_lds_size
    .group_segment_fixed_size: 0
    .kernarg_segment_align: 8
    .kernarg_segment_size: 432
    .language:       OpenCL C
    .language_version:
      - 2
      - 0
    .max_flat_workgroup_size: 512
    .name:           _Z14fwd_megakernel4Args
    .private_segment_fixed_size: 0
    .sgpr_count:     106
    .sgpr_spill_count: 117
    .symbol:         _Z14fwd_megakernel4Args.kd
    .uniform_work_group_size: 1
    .uses_dynamic_stack: false
    .vgpr_count:     242
    .vgpr_spill_count: 0
    .wavefront_size: 64
